# skip the post-MFMA s_nop on the hoisted far-tile QK2 path
# baseline (speedup 1.0000x reference)
; __device__ __forceinline__ float xhalf_max(float m) { auto rr = __builtin_amdgcn_permlane32_swap(__float_as_uint(m), __float_as_uint(m), false, false); return fmaxf(__uint_as_float(rr[0]), __uint_as_float(rr[1])); }
; __device__ __forceinline__ void softmax_def(f32x16& p0, f32x16& p1, bool first, float cb, float& mref, f32x16& negm, float& l, f32x16& oa, f32x16& ob) {
;     float a = fmaxf(fmaxf(p0[0], p0[1]), p1[0]), b = fmaxf(fmaxf(p0[2], p0[3]), p1[1]);
;     a = fmaxf(fmaxf(a, p1[2]), p1[3]);
; #pragma unroll
;     for (int r = 4; r < 16; r += 4) { a = fmaxf(fmaxf(a, p0[r]), p0[r + 1]); b = fmaxf(fmaxf(b, p0[r + 2]), p0[r + 3]); a = fmaxf(fmaxf(a, p1[r]), p1[r + 1]); b = fmaxf(fmaxf(b, p1[r + 2]), p1[r + 3]); }
;     const float rm = xhalf_max(fmaxf(a, b));
;     if (first || __any(rm > 16.f)) {
.Lqk2h_done_p:
	v_max_f32_e32 v4, v167, v167
	v_max_f32_e32 v76, v166, v166
	v_max_f32_e32 v4, v76, v4
	v_max3_f32 v72, v168, v169, v151
	v_max3_f32 v4, v4, v150, v152
	v_max3_f32 v4, v4, v153, v170
	v_max3_f32 v72, v72, v172, v173
	v_max3_f32 v4, v4, v171, v154
	v_max3_f32 v72, v72, v156, v157
	v_max3_f32 v4, v4, v155, v174
	v_max3_f32 v72, v72, v176, v177
	v_max3_f32 v4, v4, v175, v158
	v_max3_f32 v72, v72, v160, v161
	v_max3_f32 v4, v4, v159, v178
	v_max3_f32 v72, v72, v180, v181
	v_max3_f32 v4, v4, v179, v162
	v_max3_f32 v72, v72, v164, v165
	v_max3_f32 v4, v4, v163, v72
	v_mov_b32_e32 v72, v4
	s_nop 1
	v_permlane32_swap_b32_e32 v4, v72
	v_max_f32_e32 v72, v72, v72
	v_max_f32_e32 v4, v4, v4
	v_max_f32_e32 v72, v4, v72
	s_cbranch_vccz .LBB0_1251
	v_cmp_lt_f32_e32 vcc, s76, v72
	s_mov_b64 s[26:27], 0
	s_mov_b64 s[2:3], 0
	s_cbranch_vccz .LBB0_1246
	v_max_f32_e32 v4, v72, v72
	v_max_f32_e32 v4, 0, v4
	s_mov_b64 s[2:3], -1
